# in-proj K-loop: nt hint on A-operand (U) LDS-DMA loads to keep PROJ resident for attention
# baseline (speedup 1.0000x reference)
; #define PG8_STAGE(bufoff, gbase, voff) do { _Pragma("unroll") for (int _i = 0; _i < 2; ++_i) \
;         __builtin_amdgcn_global_load_lds((const unsigned*)((const char*)(gbase) + (voff)[_i]), (LAS unsigned*)(lds + (bufoff) + ldsw + _i * 8192), 16, 0, 0); } while (0)
; #define PG8_LDA(dst, b, h) do { _Pragma("unroll") for (int m = 0; m < 4; ++m) _Pragma("unroll") for (int k = 0; k < 2; ++k) dst[m][k] = *(const LAS bf16x8*)(lds + PG8_SA(b, h) + aoff + m * 2048 + k * 1024); } while (0)
; #define PG8_LDB(dst, b, h) do { _Pragma("unroll") for (int n = 0; n < 2; ++n) _Pragma("unroll") for (int k = 0; k < 2; ++k) dst[n][k] = *(const LAS bf16x8*)(lds + PG8_SB(b, h) + boff + n * 2048 + k * 1024); } while (0)
; #define PG8_WAIT_V(n) asm volatile("s_waitcnt vmcnt(" #n ")" ::: "memory")
; #define PG8_WAIT_L(n) asm volatile("s_waitcnt lgkmcnt(" #n ")" ::: "memory")
; #define PG8_BAR __builtin_amdgcn_s_barrier()
; #define PG8_SCHED __builtin_amdgcn_sched_barrier(0)
; template <class Epi>
; __device__ __forceinline__ void gemm_phase(LAS unsigned char* lds, const Gemm g, const StaticOrder& S, const Epi& E) {
;     ...
;         const bool has_next = S.next(ui + 1, nxt);
;         const char* nA = has_next ? (const char*)g.A + (size_t)nxt.pm * tstepA : cA; const char* nB = has_next ? (const char*)g.Bt + (size_t)nxt.pn * tstepB : cB;
;         for (int t = 0; t < nt; t += 2) {
;             const bool last = (t == nt - 2);
;             const char* a1 = cA + (size_t)(t + 1) * kstep;
;             const char* a2 = last ? nA : cA + (size_t)(t + 2) * kstep; const char* b2 = last ? nB : cB + (size_t)(t + 2) * kstep;
;             const char* a3 = a2 + kstep; const char* b3 = b2 + kstep;
;             PG8_LDB(B0, 0, 0); PG8_SCHED; PG8_LDA(At, 0, 0); PG8_STAGE(PG8_SA(1, 1), a1 + hstepA, voffA);
;             PG8_WAIT_L(8); PG8_BAR; PG8_WAIT_L(0); PG8_MMA(0, 0, At, B0); PG8_BAR; PG8_SCHED;
;             PG8_LDB(B1, 0, 1); PG8_STAGE(PG8_SB(0, 0), b2, voffB);
;             PG8_BAR; PG8_WAIT_L(0); PG8_MMA(0, 1, At, B1); PG8_BAR;
;             PG8_LDA(At, 0, 1); PG8_STAGE(PG8_SA(0, 0), a2, voffA);
;             PG8_BAR; PG8_WAIT_L(0); PG8_MMA(1, 0, At, B0); PG8_BAR; PG8_SCHED;
;             PG8_STAGE(PG8_SB(0, 1), b2 + hstepB, voffB);
;             PG8_WAIT_V(6); PG8_BAR; PG8_MMA(1, 1, At, B1); PG8_BAR;
.LBB0_246:
	s_ashr_i32 s5, s4, 31
	v_cmp_lt_i64_e32 vcc, s[6:7], v[154:155]
	s_lshl_b64 s[6:7], s[4:5], 20
	v_readlane_b32 s8, v252, 53
	v_readlane_b32 s9, v252, 54
	s_add_u32 s6, s8, s6
	s_addc_u32 s7, s9, s7
	s_and_b64 s[8:9], vcc, exec
	s_cselect_b32 s5, s7, s13
	s_cselect_b32 s11, s6, s12
	s_ashr_i32 s3, s2, 31
	s_lshl_b64 s[8:9], s[2:3], 20
	s_add_u32 s8, s21, s8
	s_addc_u32 s9, s22, s9
	s_and_b64 s[16:17], vcc, exec
	s_cselect_b32 s3, s9, s15
	s_cselect_b32 s35, s8, s14
	s_add_u32 s12, s12, 0x84000
	s_addc_u32 s13, s13, 0
	s_add_u32 s36, s14, 0x8000
	s_addc_u32 s37, s15, 0
	s_mov_b32 s38, -2
	s_add_u32 s14, s12, 0xfff84000
	s_addc_u32 s15, s13, -1
	s_cmp_eq_u32 s38, 28
	s_cselect_b32 s18, s11, s14
	s_cselect_b32 s19, s5, s15
	s_cselect_b32 s14, s35, s36
	s_cselect_b32 s15, s3, s37
	s_add_u32 s16, s18, 0x4000
	s_addc_u32 s17, s19, 0
	s_add_i32 m0, s25, 0xc000
	v_lshl_add_u64 v[194:195], s[12:13], 0, v[156:157]
	global_load_lds_dwordx4 v[194:195], off nt
	s_add_i32 m0, s25, 0xe000
	v_lshl_add_u64 v[194:195], s[12:13], 0, v[158:159]
	global_load_lds_dwordx4 v[194:195], off nt
	s_mov_b32 s39, 0x10000
	v_add_u32_e32 v140, s39, v170
	ds_read_b128 v[128:131], v140
	ds_read_b128 v[136:139], v140 offset:2048
	ds_read_b128 v[132:135], v140 offset:1024
	ds_read_b128 v[140:143], v140 offset:3072
	ds_read_b128 v[144:147], v172
	ds_read_b128 v[166:169], v172 offset:2048
	ds_read_b128 v[178:181], v172 offset:4096
	ds_read_b128 v[186:189], v172 offset:6144
	ds_read_b128 v[148:151], v172 offset:1024
	ds_read_b128 v[174:177], v172 offset:3072
	ds_read_b128 v[182:185], v172 offset:5120
	ds_read_b128 v[190:193], v172 offset:7168
	s_mov_b32 s42, 0x14000
	s_add_i32 s39, s39, s23
	v_add_u32_e32 v152, s42, v170
	ds_read_b128 v[194:197], v152
	ds_read_b128 v[202:205], v152 offset:2048
	ds_read_b128 v[198:201], v152 offset:1024
	ds_read_b128 v[206:209], v152 offset:3072
	s_waitcnt lgkmcnt(0)
	s_barrier
	v_mfma_f32_16x16x32_bf16 v[124:127], v[128:131], v[144:147], 0
	s_setprio 1
	v_mfma_f32_16x16x32_bf16 v[120:123], v[136:139], v[144:147], 0
	v_mfma_f32_16x16x32_bf16 v[108:111], v[128:131], v[166:169], 0
	v_mfma_f32_16x16x32_bf16 v[104:107], v[136:139], v[166:169], 0
	v_mfma_f32_16x16x32_bf16 v[92:95], v[128:131], v[178:181], 0
	v_mfma_f32_16x16x32_bf16 v[88:91], v[136:139], v[178:181], 0
	v_mfma_f32_16x16x32_bf16 v[76:79], v[128:131], v[186:189], 0
	v_mfma_f32_16x16x32_bf16 v[72:75], v[136:139], v[186:189], 0
	v_mfma_f32_16x16x32_bf16 v[124:127], v[132:135], v[148:151], v[124:127]
	v_mfma_f32_16x16x32_bf16 v[120:123], v[140:143], v[148:151], v[120:123]
	v_mfma_f32_16x16x32_bf16 v[108:111], v[132:135], v[174:177], v[108:111]
	v_mfma_f32_16x16x32_bf16 v[104:107], v[140:143], v[174:177], v[104:107]
	v_mfma_f32_16x16x32_bf16 v[92:95], v[132:135], v[182:185], v[92:95]
	v_mfma_f32_16x16x32_bf16 v[88:91], v[140:143], v[182:185], v[88:91]
	v_mfma_f32_16x16x32_bf16 v[76:79], v[132:135], v[190:193], v[76:79]
	v_mfma_f32_16x16x32_bf16 v[72:75], v[140:143], v[190:193], v[72:75]
	v_mfma_f32_16x16x32_bf16 v[116:119], v[194:197], v[144:147], 0
	v_mfma_f32_16x16x32_bf16 v[112:115], v[202:205], v[144:147], 0
	v_mfma_f32_16x16x32_bf16 v[100:103], v[194:197], v[166:169], 0
	v_mfma_f32_16x16x32_bf16 v[96:99], v[202:205], v[166:169], 0
	v_mfma_f32_16x16x32_bf16 v[84:87], v[194:197], v[178:181], 0
	v_mfma_f32_16x16x32_bf16 v[80:83], v[202:205], v[178:181], 0
	v_mfma_f32_16x16x32_bf16 v[68:71], v[194:197], v[186:189], 0
	v_mfma_f32_16x16x32_bf16 v[64:67], v[202:205], v[186:189], 0
	v_mfma_f32_16x16x32_bf16 v[116:119], v[198:201], v[148:151], v[116:119]
	v_mfma_f32_16x16x32_bf16 v[112:115], v[206:209], v[148:151], v[112:115]
	v_mfma_f32_16x16x32_bf16 v[100:103], v[198:201], v[174:177], v[100:103]
	v_mfma_f32_16x16x32_bf16 v[96:99], v[206:209], v[174:177], v[96:99]
	v_mfma_f32_16x16x32_bf16 v[84:87], v[198:201], v[182:185], v[84:87]
	v_mfma_f32_16x16x32_bf16 v[80:83], v[206:209], v[182:185], v[80:83]
	v_mfma_f32_16x16x32_bf16 v[68:71], v[198:201], v[190:193], v[68:71]
	s_setprio 0
	v_mfma_f32_16x16x32_bf16 v[64:67], v[206:209], v[190:193], v[64:67]
	s_barrier
	s_mov_b32 m0, s39
	v_lshl_add_u64 v[210:211], s[14:15], 0, v[156:157]
	global_load_lds_dwordx4 v[210:211], off
	s_add_i32 m0, s39, 0x2000
	v_lshl_add_u64 v[210:211], s[14:15], 0, v[158:159]
	global_load_lds_dwordx4 v[210:211], off
	s_mov_b32 m0, s25
	v_lshl_add_u64 v[210:211], s[18:19], 0, v[156:157]
	global_load_lds_dwordx4 v[210:211], off nt
	s_mov_b32 m0, s26
	v_lshl_add_u64 v[210:211], s[18:19], 0, v[158:159]
	global_load_lds_dwordx4 v[210:211], off nt
	s_add_u32 s40, s14, 0x80000
	s_addc_u32 s41, s15, 0
	s_add_i32 s39, s42, s23
	s_mov_b32 m0, s39
	v_lshl_add_u64 v[210:211], s[40:41], 0, v[156:157]
	global_load_lds_dwordx4 v[210:211], off
	s_add_i32 m0, s39, 0x2000
	v_lshl_add_u64 v[210:211], s[40:41], 0, v[158:159]
	global_load_lds_dwordx4 v[210:211], off
	ds_read_b128 v[144:147], v172 offset:16384
	ds_read_b128 v[166:169], v172 offset:18432
	ds_read_b128 v[178:181], v172 offset:20480
	ds_read_b128 v[186:189], v172 offset:22528
	ds_read_b128 v[148:151], v172 offset:17408
	ds_read_b128 v[174:177], v172 offset:19456
	ds_read_b128 v[182:185], v172 offset:21504
	ds_read_b128 v[190:193], v172 offset:23552
	s_waitcnt vmcnt(6)
	s_waitcnt lgkmcnt(0)
	s_barrier
; #define PG8_STAGE(bufoff, gbase, voff) do { _Pragma("unroll") for (int _i = 0; _i < 2; ++_i) \
;         __builtin_amdgcn_global_load_lds((const unsigned*)((const char*)(gbase) + (voff)[_i]), (LAS unsigned*)(lds + (bufoff) + ldsw + _i * 8192), 16, 0, 0); } while (0)
; #define PG8_LDA(dst, b, h) do { _Pragma("unroll") for (int m = 0; m < 4; ++m) _Pragma("unroll") for (int k = 0; k < 2; ++k) dst[m][k] = *(const LAS bf16x8*)(lds + PG8_SA(b, h) + aoff + m * 2048 + k * 1024); } while (0)
; #define PG8_LDB(dst, b, h) do { _Pragma("unroll") for (int n = 0; n < 2; ++n) _Pragma("unroll") for (int k = 0; k < 2; ++k) dst[n][k] = *(const LAS bf16x8*)(lds + PG8_SB(b, h) + boff + n * 2048 + k * 1024); } while (0)
; #define PG8_MMA(ai, bj, At, Bt) do { __builtin_amdgcn_s_setprio(1); _Pragma("unroll") for (int m = 0; m < 4; ++m) _Pragma("unroll") for (int n = 0; n < 2; ++n) _Pragma("unroll") for (int k = 0; k < 2; ++k) \
;         acc[ai][bj][m][n] = __builtin_amdgcn_mfma_f32_16x16x32_bf16(Bt[n][k], At[m][k], acc[ai][bj][m][n], 0, 0, 0); __builtin_amdgcn_s_setprio(0); } while (0)
; #define PG8_WAIT_V(n) asm volatile("s_waitcnt vmcnt(" #n ")" ::: "memory")
; #define PG8_WAIT_L(n) asm volatile("s_waitcnt lgkmcnt(" #n ")" ::: "memory")
; #define PG8_BAR __builtin_amdgcn_s_barrier()
; #define PG8_SCHED __builtin_amdgcn_sched_barrier(0)
; template <class Epi>
; __device__ __forceinline__ void gemm_phase(LAS unsigned char* lds, const Gemm g, const StaticOrder& S, const Epi& E) {
;     ...
;             PG8_BAR; PG8_WAIT_L(0); PG8_MMA(1, 0, At, B0); PG8_BAR; PG8_SCHED;
;             PG8_STAGE(PG8_SB(0, 1), b2 + hstepB, voffB);
;             PG8_WAIT_V(6); PG8_BAR; PG8_MMA(1, 1, At, B1); PG8_BAR;
;             PG8_LDB(B0, 1, 0); PG8_SCHED; PG8_LDA(At, 1, 0); PG8_STAGE(PG8_SA(0, 1), a2 + hstepA, voffA);
;             PG8_WAIT_L(8); PG8_BAR; PG8_WAIT_L(0); PG8_MMA(0, 0, At, B0); PG8_BAR; PG8_SCHED;
;             PG8_LDB(B1, 1, 1); PG8_STAGE(PG8_SB(1, 0), b3, voffB);
;             PG8_BAR; PG8_WAIT_L(0); PG8_MMA(0, 1, At, B1); PG8_BAR;
	v_mfma_f32_16x16x32_bf16 v[60:63], v[128:131], v[144:147], 0
	s_setprio 1
	v_mfma_f32_16x16x32_bf16 v[56:59], v[136:139], v[144:147], 0
	v_mfma_f32_16x16x32_bf16 v[44:47], v[128:131], v[166:169], 0
	v_mfma_f32_16x16x32_bf16 v[40:43], v[136:139], v[166:169], 0
	v_mfma_f32_16x16x32_bf16 v[28:31], v[128:131], v[178:181], 0
	v_mfma_f32_16x16x32_bf16 v[24:27], v[136:139], v[178:181], 0
	v_mfma_f32_16x16x32_bf16 v[12:15], v[128:131], v[186:189], 0
	v_mfma_f32_16x16x32_bf16 v[8:11], v[136:139], v[186:189], 0
	v_mfma_f32_16x16x32_bf16 v[60:63], v[132:135], v[148:151], v[60:63]
	v_mfma_f32_16x16x32_bf16 v[56:59], v[140:143], v[148:151], v[56:59]
	v_mfma_f32_16x16x32_bf16 v[44:47], v[132:135], v[174:177], v[44:47]
	v_mfma_f32_16x16x32_bf16 v[40:43], v[140:143], v[174:177], v[40:43]
	v_mfma_f32_16x16x32_bf16 v[28:31], v[132:135], v[182:185], v[28:31]
	v_mfma_f32_16x16x32_bf16 v[24:27], v[140:143], v[182:185], v[24:27]
	v_mfma_f32_16x16x32_bf16 v[12:15], v[132:135], v[190:193], v[12:15]
	v_mfma_f32_16x16x32_bf16 v[8:11], v[140:143], v[190:193], v[8:11]
	v_mfma_f32_16x16x32_bf16 v[52:55], v[194:197], v[144:147], 0
	v_mfma_f32_16x16x32_bf16 v[48:51], v[202:205], v[144:147], 0
	s_add_i32 s39, 0, 0x18000
	v_add_u32_e32 v140, s39, v170
	v_mfma_f32_16x16x32_bf16 v[36:39], v[194:197], v[166:169], 0
	v_mfma_f32_16x16x32_bf16 v[32:35], v[202:205], v[166:169], 0
	v_mfma_f32_16x16x32_bf16 v[20:23], v[194:197], v[178:181], 0
	v_mfma_f32_16x16x32_bf16 v[16:19], v[202:205], v[178:181], 0
	v_mfma_f32_16x16x32_bf16 v[4:7], v[194:197], v[186:189], 0
	v_mfma_f32_16x16x32_bf16 v[0:3], v[202:205], v[186:189], 0
	v_mfma_f32_16x16x32_bf16 v[52:55], v[198:201], v[148:151], v[52:55]
	v_mfma_f32_16x16x32_bf16 v[48:51], v[206:209], v[148:151], v[48:51]
	v_mfma_f32_16x16x32_bf16 v[36:39], v[198:201], v[174:177], v[36:39]
	v_mfma_f32_16x16x32_bf16 v[32:35], v[206:209], v[174:177], v[32:35]
	v_mfma_f32_16x16x32_bf16 v[20:23], v[198:201], v[182:185], v[20:23]
	v_mfma_f32_16x16x32_bf16 v[16:19], v[206:209], v[182:185], v[16:19]
	v_mfma_f32_16x16x32_bf16 v[4:7], v[198:201], v[190:193], v[4:7]
	s_setprio 0
	v_mfma_f32_16x16x32_bf16 v[0:3], v[206:209], v[190:193], v[0:3]
	s_barrier
	s_add_u32 s18, s18, 0x80000
	s_addc_u32 s19, s19, 0
	s_mov_b32 m0, s27
	v_lshl_add_u64 v[194:195], s[18:19], 0, v[156:157]
	global_load_lds_dwordx4 v[194:195], off nt
	s_mov_b32 m0, s28
	v_lshl_add_u64 v[194:195], s[18:19], 0, v[158:159]
	global_load_lds_dwordx4 v[194:195], off nt
	ds_read_b128 v[128:131], v140
	ds_read_b128 v[136:139], v140 offset:2048
	ds_read_b128 v[132:135], v140 offset:1024
	ds_read_b128 v[140:143], v140 offset:3072
	ds_read_b128 v[144:147], v172 offset:32768
	ds_read_b128 v[166:169], v172 offset:34816
	ds_read_b128 v[178:181], v172 offset:36864
	ds_read_b128 v[186:189], v172 offset:38912
	ds_read_b128 v[148:151], v172 offset:33792
	ds_read_b128 v[174:177], v172 offset:35840
	ds_read_b128 v[182:185], v172 offset:37888
	ds_read_b128 v[190:193], v172 offset:39936
	s_mov_b32 s40, 0x1c000
	s_add_u32 s18, s14, 0x4000
	s_addc_u32 s19, s15, 0
	s_add_i32 s39, s39, s23
	v_add_u32_e32 v152, s40, v170
	ds_read_b128 v[194:197], v152
	ds_read_b128 v[202:205], v152 offset:2048
	ds_read_b128 v[198:201], v152 offset:1024
	ds_read_b128 v[206:209], v152 offset:3072
	s_waitcnt lgkmcnt(0)
	s_barrier
	v_mfma_f32_16x16x32_bf16 v[124:127], v[128:131], v[144:147], v[124:127]
	s_setprio 1
	v_mfma_f32_16x16x32_bf16 v[120:123], v[136:139], v[144:147], v[120:123]
	v_mfma_f32_16x16x32_bf16 v[108:111], v[128:131], v[166:169], v[108:111]
	v_mfma_f32_16x16x32_bf16 v[104:107], v[136:139], v[166:169], v[104:107]
	v_mfma_f32_16x16x32_bf16 v[92:95], v[128:131], v[178:181], v[92:95]
	v_mfma_f32_16x16x32_bf16 v[88:91], v[136:139], v[178:181], v[88:91]
	v_mfma_f32_16x16x32_bf16 v[76:79], v[128:131], v[186:189], v[76:79]
	v_mfma_f32_16x16x32_bf16 v[72:75], v[136:139], v[186:189], v[72:75]
	v_mfma_f32_16x16x32_bf16 v[124:127], v[132:135], v[148:151], v[124:127]
	v_mfma_f32_16x16x32_bf16 v[120:123], v[140:143], v[148:151], v[120:123]
	v_mfma_f32_16x16x32_bf16 v[108:111], v[132:135], v[174:177], v[108:111]
	v_mfma_f32_16x16x32_bf16 v[104:107], v[140:143], v[174:177], v[104:107]
	v_mfma_f32_16x16x32_bf16 v[92:95], v[132:135], v[182:185], v[92:95]
	v_mfma_f32_16x16x32_bf16 v[88:91], v[140:143], v[182:185], v[88:91]
	v_mfma_f32_16x16x32_bf16 v[76:79], v[132:135], v[190:193], v[76:79]
	v_mfma_f32_16x16x32_bf16 v[72:75], v[140:143], v[190:193], v[72:75]
	v_mfma_f32_16x16x32_bf16 v[116:119], v[194:197], v[144:147], v[116:119]
	v_mfma_f32_16x16x32_bf16 v[112:115], v[202:205], v[144:147], v[112:115]
	v_mfma_f32_16x16x32_bf16 v[100:103], v[194:197], v[166:169], v[100:103]
	v_mfma_f32_16x16x32_bf16 v[96:99], v[202:205], v[166:169], v[96:99]
	v_mfma_f32_16x16x32_bf16 v[84:87], v[194:197], v[178:181], v[84:87]
	v_mfma_f32_16x16x32_bf16 v[80:83], v[202:205], v[178:181], v[80:83]
	v_mfma_f32_16x16x32_bf16 v[68:71], v[194:197], v[186:189], v[68:71]
	v_mfma_f32_16x16x32_bf16 v[64:67], v[202:205], v[186:189], v[64:67]
	v_mfma_f32_16x16x32_bf16 v[116:119], v[198:201], v[148:151], v[116:119]
	v_mfma_f32_16x16x32_bf16 v[112:115], v[206:209], v[148:151], v[112:115]
	v_mfma_f32_16x16x32_bf16 v[100:103], v[198:201], v[174:177], v[100:103]
	v_mfma_f32_16x16x32_bf16 v[96:99], v[206:209], v[174:177], v[96:99]
	v_mfma_f32_16x16x32_bf16 v[84:87], v[198:201], v[182:185], v[84:87]
	v_mfma_f32_16x16x32_bf16 v[80:83], v[206:209], v[182:185], v[80:83]
	v_mfma_f32_16x16x32_bf16 v[68:71], v[198:201], v[190:193], v[68:71]
	s_setprio 0
	v_mfma_f32_16x16x32_bf16 v[64:67], v[206:209], v[190:193], v[64:67]
	s_barrier
; #define PG8_STAGE(bufoff, gbase, voff) do { _Pragma("unroll") for (int _i = 0; _i < 2; ++_i) \
;         __builtin_amdgcn_global_load_lds((const unsigned*)((const char*)(gbase) + (voff)[_i]), (LAS unsigned*)(lds + (bufoff) + ldsw + _i * 8192), 16, 0, 0); } while (0)
; #define PG8_LDA(dst, b, h) do { _Pragma("unroll") for (int m = 0; m < 4; ++m) _Pragma("unroll") for (int k = 0; k < 2; ++k) dst[m][k] = *(const LAS bf16x8*)(lds + PG8_SA(b, h) + aoff + m * 2048 + k * 1024); } while (0)
; #define PG8_LDB(dst, b, h) do { _Pragma("unroll") for (int n = 0; n < 2; ++n) _Pragma("unroll") for (int k = 0; k < 2; ++k) dst[n][k] = *(const LAS bf16x8*)(lds + PG8_SB(b, h) + boff + n * 2048 + k * 1024); } while (0)
; #define PG8_MMA(ai, bj, At, Bt) do { __builtin_amdgcn_s_setprio(1); _Pragma("unroll") for (int m = 0; m < 4; ++m) _Pragma("unroll") for (int n = 0; n < 2; ++n) _Pragma("unroll") for (int k = 0; k < 2; ++k) \
;         acc[ai][bj][m][n] = __builtin_amdgcn_mfma_f32_16x16x32_bf16(Bt[n][k], At[m][k], acc[ai][bj][m][n], 0, 0, 0); __builtin_amdgcn_s_setprio(0); } while (0)
; #define PG8_WAIT_V(n) asm volatile("s_waitcnt vmcnt(" #n ")" ::: "memory")
; #define PG8_WAIT_L(n) asm volatile("s_waitcnt lgkmcnt(" #n ")" ::: "memory")
; #define PG8_BAR __builtin_amdgcn_s_barrier()
; #define PG8_SCHED __builtin_amdgcn_sched_barrier(0)
; template <class Epi>
; __device__ __forceinline__ void gemm_phase(LAS unsigned char* lds, const Gemm g, const StaticOrder& S, const Epi& E) {
;     ...
;             PG8_LDB(B0, 0, 0); PG8_SCHED; PG8_LDA(At, 0, 0); PG8_STAGE(PG8_SA(1, 1), a1 + hstepA, voffA);
;     ...
;             PG8_LDA(At, 1, 1); PG8_STAGE(PG8_SA(1, 0), a3, voffA);
;             PG8_BAR; PG8_WAIT_L(0); PG8_MMA(1, 0, At, B0); PG8_BAR; PG8_SCHED;
;             PG8_STAGE(PG8_SB(1, 1), b3 + hstepB, voffB);
;             PG8_WAIT_V(6); PG8_BAR; PG8_MMA(1, 1, At, B1); PG8_BAR;
	s_mov_b32 m0, s39
	v_lshl_add_u64 v[210:211], s[18:19], 0, v[156:157]
	global_load_lds_dwordx4 v[210:211], off
	s_add_i32 m0, s39, 0x2000
	v_lshl_add_u64 v[210:211], s[18:19], 0, v[158:159]
	global_load_lds_dwordx4 v[210:211], off
	s_mov_b32 m0, s29
	v_lshl_add_u64 v[210:211], s[16:17], 0, v[156:157]
	global_load_lds_dwordx4 v[210:211], off nt
	s_mov_b32 m0, s30
	v_lshl_add_u64 v[210:211], s[16:17], 0, v[158:159]
	global_load_lds_dwordx4 v[210:211], off nt
	s_add_u32 s14, s14, 0x84000
	s_addc_u32 s15, s15, 0
	s_add_i32 s16, s40, s23
	s_mov_b32 m0, s16
	v_lshl_add_u64 v[210:211], s[14:15], 0, v[156:157]
	global_load_lds_dwordx4 v[210:211], off
	s_add_i32 m0, s16, 0x2000
	v_lshl_add_u64 v[210:211], s[14:15], 0, v[158:159]
	global_load_lds_dwordx4 v[210:211], off
	ds_read_b128 v[144:147], v172 offset:49152
	ds_read_b128 v[166:169], v172 offset:51200
	ds_read_b128 v[178:181], v172 offset:53248
	ds_read_b128 v[186:189], v172 offset:55296
	ds_read_b128 v[148:151], v172 offset:50176
	ds_read_b128 v[174:177], v172 offset:52224
	ds_read_b128 v[182:185], v172 offset:54272
	ds_read_b128 v[190:193], v172 offset:56320
	s_waitcnt vmcnt(6)
	s_waitcnt lgkmcnt(0)
	s_barrier
	v_mfma_f32_16x16x32_bf16 v[60:63], v[128:131], v[144:147], v[60:63]
	s_setprio 1
	v_mfma_f32_16x16x32_bf16 v[56:59], v[136:139], v[144:147], v[56:59]
	v_mfma_f32_16x16x32_bf16 v[44:47], v[128:131], v[166:169], v[44:47]
	v_mfma_f32_16x16x32_bf16 v[40:43], v[136:139], v[166:169], v[40:43]
	v_mfma_f32_16x16x32_bf16 v[28:31], v[128:131], v[178:181], v[28:31]
	v_mfma_f32_16x16x32_bf16 v[24:27], v[136:139], v[178:181], v[24:27]
	v_mfma_f32_16x16x32_bf16 v[12:15], v[128:131], v[186:189], v[12:15]
	v_mfma_f32_16x16x32_bf16 v[8:11], v[136:139], v[186:189], v[8:11]
	v_mfma_f32_16x16x32_bf16 v[60:63], v[132:135], v[148:151], v[60:63]
	v_mfma_f32_16x16x32_bf16 v[56:59], v[140:143], v[148:151], v[56:59]
	v_mfma_f32_16x16x32_bf16 v[44:47], v[132:135], v[174:177], v[44:47]
	v_mfma_f32_16x16x32_bf16 v[40:43], v[140:143], v[174:177], v[40:43]
	v_mfma_f32_16x16x32_bf16 v[28:31], v[132:135], v[182:185], v[28:31]
	v_mfma_f32_16x16x32_bf16 v[24:27], v[140:143], v[182:185], v[24:27]
	v_mfma_f32_16x16x32_bf16 v[12:15], v[132:135], v[190:193], v[12:15]
	v_mfma_f32_16x16x32_bf16 v[8:11], v[140:143], v[190:193], v[8:11]
	v_mfma_f32_16x16x32_bf16 v[52:55], v[194:197], v[144:147], v[52:55]
	v_mfma_f32_16x16x32_bf16 v[48:51], v[202:205], v[144:147], v[48:51]
	s_add_i32 s38, s38, 2
	s_add_u32 s12, s12, 0x8000
	s_addc_u32 s13, s13, 0
	s_add_u32 s36, s36, 0x8000
	s_addc_u32 s37, s37, 0
	v_mfma_f32_16x16x32_bf16 v[36:39], v[194:197], v[166:169], v[36:39]
	v_mfma_f32_16x16x32_bf16 v[32:35], v[202:205], v[166:169], v[32:35]
	v_mfma_f32_16x16x32_bf16 v[20:23], v[194:197], v[178:181], v[20:23]
	v_mfma_f32_16x16x32_bf16 v[16:19], v[202:205], v[178:181], v[16:19]
	v_mfma_f32_16x16x32_bf16 v[4:7], v[194:197], v[186:189], v[4:7]
	v_mfma_f32_16x16x32_bf16 v[0:3], v[202:205], v[186:189], v[0:3]
	v_mfma_f32_16x16x32_bf16 v[52:55], v[198:201], v[148:151], v[52:55]
	v_mfma_f32_16x16x32_bf16 v[48:51], v[206:209], v[148:151], v[48:51]
	v_mfma_f32_16x16x32_bf16 v[36:39], v[198:201], v[174:177], v[36:39]
	v_mfma_f32_16x16x32_bf16 v[32:35], v[206:209], v[174:177], v[32:35]
	v_mfma_f32_16x16x32_bf16 v[20:23], v[198:201], v[182:185], v[20:23]
	v_mfma_f32_16x16x32_bf16 v[16:19], v[206:209], v[182:185], v[16:19]
	v_mfma_f32_16x16x32_bf16 v[4:7], v[198:201], v[190:193], v[4:7]
	s_cmp_gt_u32 s38, 29
	s_setprio 0
	v_mfma_f32_16x16x32_bf16 v[0:3], v[206:209], v[190:193], v[0:3]
	s_barrier
	s_cbranch_scc0 .LBB0_247
	s_branch .Lpeel_done_247
.LBB0_247:
	s_add_u32 s14, s12, 0xfff84000
	s_addc_u32 s15, s13, -1
	s_cmp_eq_u32 s38, 28
	s_cselect_b32 s18, s11, s14
	s_cselect_b32 s19, s5, s15
	s_cselect_b32 s14, s35, s36
	s_cselect_b32 s15, s3, s37
	s_add_u32 s16, s18, 0x4000
	s_addc_u32 s17, s19, 0
	s_add_i32 m0, s25, 0xc000
	v_lshl_add_u64 v[194:195], s[12:13], 0, v[156:157]
	global_load_lds_dwordx4 v[194:195], off nt
	s_add_i32 m0, s25, 0xe000
	v_lshl_add_u64 v[194:195], s[12:13], 0, v[158:159]
	global_load_lds_dwordx4 v[194:195], off nt
	s_mov_b32 s39, 0x10000
	v_add_u32_e32 v140, s39, v170
	ds_read_b128 v[128:131], v140
	ds_read_b128 v[136:139], v140 offset:2048
	ds_read_b128 v[132:135], v140 offset:1024
	ds_read_b128 v[140:143], v140 offset:3072
	ds_read_b128 v[144:147], v172
	ds_read_b128 v[166:169], v172 offset:2048
	ds_read_b128 v[178:181], v172 offset:4096
	ds_read_b128 v[186:189], v172 offset:6144
	ds_read_b128 v[148:151], v172 offset:1024
	ds_read_b128 v[174:177], v172 offset:3072
	ds_read_b128 v[182:185], v172 offset:5120
	ds_read_b128 v[190:193], v172 offset:7168
	s_mov_b32 s42, 0x14000
	s_add_i32 s39, s39, s23
	v_add_u32_e32 v152, s42, v170
	ds_read_b128 v[194:197], v152
	ds_read_b128 v[202:205], v152 offset:2048
	ds_read_b128 v[198:201], v152 offset:1024
	ds_read_b128 v[206:209], v152 offset:3072
	s_waitcnt lgkmcnt(0)
	s_barrier
; #define PG8_STAGE(bufoff, gbase, voff) do { _Pragma("unroll") for (int _i = 0; _i < 2; ++_i) \
;         __builtin_amdgcn_global_load_lds((const unsigned*)((const char*)(gbase) + (voff)[_i]), (LAS unsigned*)(lds + (bufoff) + ldsw + _i * 8192), 16, 0, 0); } while (0)
; #define PG8_LDA(dst, b, h) do { _Pragma("unroll") for (int m = 0; m < 4; ++m) _Pragma("unroll") for (int k = 0; k < 2; ++k) dst[m][k] = *(const LAS bf16x8*)(lds + PG8_SA(b, h) + aoff + m * 2048 + k * 1024); } while (0)
; #define PG8_LDB(dst, b, h) do { _Pragma("unroll") for (int n = 0; n < 2; ++n) _Pragma("unroll") for (int k = 0; k < 2; ++k) dst[n][k] = *(const LAS bf16x8*)(lds + PG8_SB(b, h) + boff + n * 2048 + k * 1024); } while (0)
; #define PG8_MMA(ai, bj, At, Bt) do { __builtin_amdgcn_s_setprio(1); _Pragma("unroll") for (int m = 0; m < 4; ++m) _Pragma("unroll") for (int n = 0; n < 2; ++n) _Pragma("unroll") for (int k = 0; k < 2; ++k) \
;         acc[ai][bj][m][n] = __builtin_amdgcn_mfma_f32_16x16x32_bf16(Bt[n][k], At[m][k], acc[ai][bj][m][n], 0, 0, 0); __builtin_amdgcn_s_setprio(0); } while (0)
; #define PG8_WAIT_V(n) asm volatile("s_waitcnt vmcnt(" #n ")" ::: "memory")
; #define PG8_WAIT_L(n) asm volatile("s_waitcnt lgkmcnt(" #n ")" ::: "memory")
; #define PG8_BAR __builtin_amdgcn_s_barrier()
; #define PG8_SCHED __builtin_amdgcn_sched_barrier(0)
; template <class Epi>
; __device__ __forceinline__ void gemm_phase(LAS unsigned char* lds, const Gemm g, const StaticOrder& S, const Epi& E) {
;     ...
;             PG8_WAIT_L(8); PG8_BAR; PG8_WAIT_L(0); PG8_MMA(0, 0, At, B0); PG8_BAR; PG8_SCHED;
;             PG8_LDB(B1, 0, 1); PG8_STAGE(PG8_SB(0, 0), b2, voffB);
;             PG8_BAR; PG8_WAIT_L(0); PG8_MMA(0, 1, At, B1); PG8_BAR;
;             PG8_LDA(At, 0, 1); PG8_STAGE(PG8_SA(0, 0), a2, voffA);
;             PG8_BAR; PG8_WAIT_L(0); PG8_MMA(1, 0, At, B0); PG8_BAR; PG8_SCHED;
;             PG8_STAGE(PG8_SB(0, 1), b2 + hstepB, voffB);
;             PG8_WAIT_V(6); PG8_BAR; PG8_MMA(1, 1, At, B1); PG8_BAR;
	v_mfma_f32_16x16x32_bf16 v[124:127], v[128:131], v[144:147], v[124:127]
	s_setprio 1
	v_mfma_f32_16x16x32_bf16 v[120:123], v[136:139], v[144:147], v[120:123]
	v_mfma_f32_16x16x32_bf16 v[108:111], v[128:131], v[166:169], v[108:111]
	v_mfma_f32_16x16x32_bf16 v[104:107], v[136:139], v[166:169], v[104:107]
	v_mfma_f32_16x16x32_bf16 v[92:95], v[128:131], v[178:181], v[92:95]
	v_mfma_f32_16x16x32_bf16 v[88:91], v[136:139], v[178:181], v[88:91]
	v_mfma_f32_16x16x32_bf16 v[76:79], v[128:131], v[186:189], v[76:79]
	v_mfma_f32_16x16x32_bf16 v[72:75], v[136:139], v[186:189], v[72:75]
	v_mfma_f32_16x16x32_bf16 v[124:127], v[132:135], v[148:151], v[124:127]
	v_mfma_f32_16x16x32_bf16 v[120:123], v[140:143], v[148:151], v[120:123]
	v_mfma_f32_16x16x32_bf16 v[108:111], v[132:135], v[174:177], v[108:111]
	v_mfma_f32_16x16x32_bf16 v[104:107], v[140:143], v[174:177], v[104:107]
	v_mfma_f32_16x16x32_bf16 v[92:95], v[132:135], v[182:185], v[92:95]
	v_mfma_f32_16x16x32_bf16 v[88:91], v[140:143], v[182:185], v[88:91]
	v_mfma_f32_16x16x32_bf16 v[76:79], v[132:135], v[190:193], v[76:79]
	v_mfma_f32_16x16x32_bf16 v[72:75], v[140:143], v[190:193], v[72:75]
	v_mfma_f32_16x16x32_bf16 v[116:119], v[194:197], v[144:147], v[116:119]
	v_mfma_f32_16x16x32_bf16 v[112:115], v[202:205], v[144:147], v[112:115]
	v_mfma_f32_16x16x32_bf16 v[100:103], v[194:197], v[166:169], v[100:103]
	v_mfma_f32_16x16x32_bf16 v[96:99], v[202:205], v[166:169], v[96:99]
	v_mfma_f32_16x16x32_bf16 v[84:87], v[194:197], v[178:181], v[84:87]
	v_mfma_f32_16x16x32_bf16 v[80:83], v[202:205], v[178:181], v[80:83]
	v_mfma_f32_16x16x32_bf16 v[68:71], v[194:197], v[186:189], v[68:71]
	v_mfma_f32_16x16x32_bf16 v[64:67], v[202:205], v[186:189], v[64:67]
	v_mfma_f32_16x16x32_bf16 v[116:119], v[198:201], v[148:151], v[116:119]
	v_mfma_f32_16x16x32_bf16 v[112:115], v[206:209], v[148:151], v[112:115]
	v_mfma_f32_16x16x32_bf16 v[100:103], v[198:201], v[174:177], v[100:103]
	v_mfma_f32_16x16x32_bf16 v[96:99], v[206:209], v[174:177], v[96:99]
	v_mfma_f32_16x16x32_bf16 v[84:87], v[198:201], v[182:185], v[84:87]
	v_mfma_f32_16x16x32_bf16 v[80:83], v[206:209], v[182:185], v[80:83]
	v_mfma_f32_16x16x32_bf16 v[68:71], v[198:201], v[190:193], v[68:71]
	s_setprio 0
	v_mfma_f32_16x16x32_bf16 v[64:67], v[206:209], v[190:193], v[64:67]
	s_barrier
	s_mov_b32 m0, s39
	v_lshl_add_u64 v[210:211], s[14:15], 0, v[156:157]
	global_load_lds_dwordx4 v[210:211], off
	s_add_i32 m0, s39, 0x2000
	v_lshl_add_u64 v[210:211], s[14:15], 0, v[158:159]
	global_load_lds_dwordx4 v[210:211], off
	s_mov_b32 m0, s25
	v_lshl_add_u64 v[210:211], s[18:19], 0, v[156:157]
	global_load_lds_dwordx4 v[210:211], off nt
	s_mov_b32 m0, s26
	v_lshl_add_u64 v[210:211], s[18:19], 0, v[158:159]
	global_load_lds_dwordx4 v[210:211], off nt
	s_add_u32 s40, s14, 0x80000
	s_addc_u32 s41, s15, 0
	s_add_i32 s39, s42, s23
	s_mov_b32 m0, s39
	v_lshl_add_u64 v[210:211], s[40:41], 0, v[156:157]
	global_load_lds_dwordx4 v[210:211], off
	s_add_i32 m0, s39, 0x2000
	v_lshl_add_u64 v[210:211], s[40:41], 0, v[158:159]
	global_load_lds_dwordx4 v[210:211], off
	ds_read_b128 v[144:147], v172 offset:16384
	ds_read_b128 v[166:169], v172 offset:18432
	ds_read_b128 v[178:181], v172 offset:20480
	ds_read_b128 v[186:189], v172 offset:22528
	ds_read_b128 v[148:151], v172 offset:17408
	ds_read_b128 v[174:177], v172 offset:19456
	ds_read_b128 v[182:185], v172 offset:21504
	ds_read_b128 v[190:193], v172 offset:23552
	s_waitcnt vmcnt(6)
	s_waitcnt lgkmcnt(0)
	s_barrier
	v_mfma_f32_16x16x32_bf16 v[60:63], v[128:131], v[144:147], v[60:63]
	s_setprio 1
	v_mfma_f32_16x16x32_bf16 v[56:59], v[136:139], v[144:147], v[56:59]
	v_mfma_f32_16x16x32_bf16 v[44:47], v[128:131], v[166:169], v[44:47]
	v_mfma_f32_16x16x32_bf16 v[40:43], v[136:139], v[166:169], v[40:43]
	v_mfma_f32_16x16x32_bf16 v[28:31], v[128:131], v[178:181], v[28:31]
	v_mfma_f32_16x16x32_bf16 v[24:27], v[136:139], v[178:181], v[24:27]
	v_mfma_f32_16x16x32_bf16 v[12:15], v[128:131], v[186:189], v[12:15]
	v_mfma_f32_16x16x32_bf16 v[8:11], v[136:139], v[186:189], v[8:11]
	v_mfma_f32_16x16x32_bf16 v[60:63], v[132:135], v[148:151], v[60:63]
	v_mfma_f32_16x16x32_bf16 v[56:59], v[140:143], v[148:151], v[56:59]
	v_mfma_f32_16x16x32_bf16 v[44:47], v[132:135], v[174:177], v[44:47]
	v_mfma_f32_16x16x32_bf16 v[40:43], v[140:143], v[174:177], v[40:43]
	v_mfma_f32_16x16x32_bf16 v[28:31], v[132:135], v[182:185], v[28:31]
	v_mfma_f32_16x16x32_bf16 v[24:27], v[140:143], v[182:185], v[24:27]
	v_mfma_f32_16x16x32_bf16 v[12:15], v[132:135], v[190:193], v[12:15]
	v_mfma_f32_16x16x32_bf16 v[8:11], v[140:143], v[190:193], v[8:11]
	v_mfma_f32_16x16x32_bf16 v[52:55], v[194:197], v[144:147], v[52:55]
	v_mfma_f32_16x16x32_bf16 v[48:51], v[202:205], v[144:147], v[48:51]
	s_add_i32 s39, 0, 0x18000
	v_add_u32_e32 v140, s39, v170
	v_mfma_f32_16x16x32_bf16 v[36:39], v[194:197], v[166:169], v[36:39]
	v_mfma_f32_16x16x32_bf16 v[32:35], v[202:205], v[166:169], v[32:35]
	v_mfma_f32_16x16x32_bf16 v[20:23], v[194:197], v[178:181], v[20:23]
	v_mfma_f32_16x16x32_bf16 v[16:19], v[202:205], v[178:181], v[16:19]
	v_mfma_f32_16x16x32_bf16 v[4:7], v[194:197], v[186:189], v[4:7]
	v_mfma_f32_16x16x32_bf16 v[0:3], v[202:205], v[186:189], v[0:3]
	v_mfma_f32_16x16x32_bf16 v[52:55], v[198:201], v[148:151], v[52:55]
	v_mfma_f32_16x16x32_bf16 v[48:51], v[206:209], v[148:151], v[48:51]
	v_mfma_f32_16x16x32_bf16 v[36:39], v[198:201], v[174:177], v[36:39]
	v_mfma_f32_16x16x32_bf16 v[32:35], v[206:209], v[174:177], v[32:35]
	v_mfma_f32_16x16x32_bf16 v[20:23], v[198:201], v[182:185], v[20:23]
	v_mfma_f32_16x16x32_bf16 v[16:19], v[206:209], v[182:185], v[16:19]
	v_mfma_f32_16x16x32_bf16 v[4:7], v[198:201], v[190:193], v[4:7]
	s_setprio 0
	v_mfma_f32_16x16x32_bf16 v[0:3], v[206:209], v[190:193], v[0:3]
	s_barrier
; #define PG8_STAGE(bufoff, gbase, voff) do { _Pragma("unroll") for (int _i = 0; _i < 2; ++_i) \
;         __builtin_amdgcn_global_load_lds((const unsigned*)((const char*)(gbase) + (voff)[_i]), (LAS unsigned*)(lds + (bufoff) + ldsw + _i * 8192), 16, 0, 0); } while (0)
; #define PG8_LDA(dst, b, h) do { _Pragma("unroll") for (int m = 0; m < 4; ++m) _Pragma("unroll") for (int k = 0; k < 2; ++k) dst[m][k] = *(const LAS bf16x8*)(lds + PG8_SA(b, h) + aoff + m * 2048 + k * 1024); } while (0)
; #define PG8_LDB(dst, b, h) do { _Pragma("unroll") for (int n = 0; n < 2; ++n) _Pragma("unroll") for (int k = 0; k < 2; ++k) dst[n][k] = *(const LAS bf16x8*)(lds + PG8_SB(b, h) + boff + n * 2048 + k * 1024); } while (0)
; #define PG8_MMA(ai, bj, At, Bt) do { __builtin_amdgcn_s_setprio(1); _Pragma("unroll") for (int m = 0; m < 4; ++m) _Pragma("unroll") for (int n = 0; n < 2; ++n) _Pragma("unroll") for (int k = 0; k < 2; ++k) \
;         acc[ai][bj][m][n] = __builtin_amdgcn_mfma_f32_16x16x32_bf16(Bt[n][k], At[m][k], acc[ai][bj][m][n], 0, 0, 0); __builtin_amdgcn_s_setprio(0); } while (0)
; #define PG8_WAIT_V(n) asm volatile("s_waitcnt vmcnt(" #n ")" ::: "memory")
; #define PG8_WAIT_L(n) asm volatile("s_waitcnt lgkmcnt(" #n ")" ::: "memory")
; #define PG8_BAR __builtin_amdgcn_s_barrier()
; #define PG8_SCHED __builtin_amdgcn_sched_barrier(0)
; template <class Epi>
; __device__ __forceinline__ void gemm_phase(LAS unsigned char* lds, const Gemm g, const StaticOrder& S, const Epi& E) {
;     ...
;             PG8_LDB(B0, 1, 0); PG8_SCHED; PG8_LDA(At, 1, 0); PG8_STAGE(PG8_SA(0, 1), a2 + hstepA, voffA);
;             PG8_WAIT_L(8); PG8_BAR; PG8_WAIT_L(0); PG8_MMA(0, 0, At, B0); PG8_BAR; PG8_SCHED;
;             PG8_LDB(B1, 1, 1); PG8_STAGE(PG8_SB(1, 0), b3, voffB);
;             PG8_BAR; PG8_WAIT_L(0); PG8_MMA(0, 1, At, B1); PG8_BAR;
;             PG8_LDA(At, 1, 1); PG8_STAGE(PG8_SA(1, 0), a3, voffA);
;             PG8_BAR; PG8_WAIT_L(0); PG8_MMA(1, 0, At, B0); PG8_BAR; PG8_SCHED;
;             PG8_STAGE(PG8_SB(1, 1), b3 + hstepB, voffB);
;             PG8_WAIT_V(6); PG8_BAR; PG8_MMA(1, 1, At, B1); PG8_BAR;
	s_add_u32 s18, s18, 0x80000
	s_addc_u32 s19, s19, 0
	s_mov_b32 m0, s27
	v_lshl_add_u64 v[194:195], s[18:19], 0, v[156:157]
	global_load_lds_dwordx4 v[194:195], off nt
	s_mov_b32 m0, s28
	v_lshl_add_u64 v[194:195], s[18:19], 0, v[158:159]
	global_load_lds_dwordx4 v[194:195], off nt
	ds_read_b128 v[128:131], v140
	ds_read_b128 v[136:139], v140 offset:2048
	ds_read_b128 v[132:135], v140 offset:1024
	ds_read_b128 v[140:143], v140 offset:3072
	ds_read_b128 v[144:147], v172 offset:32768
	ds_read_b128 v[166:169], v172 offset:34816
	ds_read_b128 v[178:181], v172 offset:36864
	ds_read_b128 v[186:189], v172 offset:38912
	ds_read_b128 v[148:151], v172 offset:33792
	ds_read_b128 v[174:177], v172 offset:35840
	ds_read_b128 v[182:185], v172 offset:37888
	ds_read_b128 v[190:193], v172 offset:39936
	s_mov_b32 s40, 0x1c000
	s_add_u32 s18, s14, 0x4000
	s_addc_u32 s19, s15, 0
	s_add_i32 s39, s39, s23
	v_add_u32_e32 v152, s40, v170
	ds_read_b128 v[194:197], v152
	ds_read_b128 v[202:205], v152 offset:2048
	ds_read_b128 v[198:201], v152 offset:1024
	ds_read_b128 v[206:209], v152 offset:3072
	s_waitcnt lgkmcnt(0)
	s_barrier
	v_mfma_f32_16x16x32_bf16 v[124:127], v[128:131], v[144:147], v[124:127]
	s_setprio 1
	v_mfma_f32_16x16x32_bf16 v[120:123], v[136:139], v[144:147], v[120:123]
	v_mfma_f32_16x16x32_bf16 v[108:111], v[128:131], v[166:169], v[108:111]
	v_mfma_f32_16x16x32_bf16 v[104:107], v[136:139], v[166:169], v[104:107]
	v_mfma_f32_16x16x32_bf16 v[92:95], v[128:131], v[178:181], v[92:95]
	v_mfma_f32_16x16x32_bf16 v[88:91], v[136:139], v[178:181], v[88:91]
	v_mfma_f32_16x16x32_bf16 v[76:79], v[128:131], v[186:189], v[76:79]
	v_mfma_f32_16x16x32_bf16 v[72:75], v[136:139], v[186:189], v[72:75]
	v_mfma_f32_16x16x32_bf16 v[124:127], v[132:135], v[148:151], v[124:127]
	v_mfma_f32_16x16x32_bf16 v[120:123], v[140:143], v[148:151], v[120:123]
	v_mfma_f32_16x16x32_bf16 v[108:111], v[132:135], v[174:177], v[108:111]
	v_mfma_f32_16x16x32_bf16 v[104:107], v[140:143], v[174:177], v[104:107]
	v_mfma_f32_16x16x32_bf16 v[92:95], v[132:135], v[182:185], v[92:95]
	v_mfma_f32_16x16x32_bf16 v[88:91], v[140:143], v[182:185], v[88:91]
	v_mfma_f32_16x16x32_bf16 v[76:79], v[132:135], v[190:193], v[76:79]
	v_mfma_f32_16x16x32_bf16 v[72:75], v[140:143], v[190:193], v[72:75]
	v_mfma_f32_16x16x32_bf16 v[116:119], v[194:197], v[144:147], v[116:119]
	v_mfma_f32_16x16x32_bf16 v[112:115], v[202:205], v[144:147], v[112:115]
	v_mfma_f32_16x16x32_bf16 v[100:103], v[194:197], v[166:169], v[100:103]
	v_mfma_f32_16x16x32_bf16 v[96:99], v[202:205], v[166:169], v[96:99]
	v_mfma_f32_16x16x32_bf16 v[84:87], v[194:197], v[178:181], v[84:87]
	v_mfma_f32_16x16x32_bf16 v[80:83], v[202:205], v[178:181], v[80:83]
	v_mfma_f32_16x16x32_bf16 v[68:71], v[194:197], v[186:189], v[68:71]
	v_mfma_f32_16x16x32_bf16 v[64:67], v[202:205], v[186:189], v[64:67]
	v_mfma_f32_16x16x32_bf16 v[116:119], v[198:201], v[148:151], v[116:119]
	v_mfma_f32_16x16x32_bf16 v[112:115], v[206:209], v[148:151], v[112:115]
	v_mfma_f32_16x16x32_bf16 v[100:103], v[198:201], v[174:177], v[100:103]
	v_mfma_f32_16x16x32_bf16 v[96:99], v[206:209], v[174:177], v[96:99]
	v_mfma_f32_16x16x32_bf16 v[84:87], v[198:201], v[182:185], v[84:87]
	v_mfma_f32_16x16x32_bf16 v[80:83], v[206:209], v[182:185], v[80:83]
	v_mfma_f32_16x16x32_bf16 v[68:71], v[198:201], v[190:193], v[68:71]
	s_setprio 0
	v_mfma_f32_16x16x32_bf16 v[64:67], v[206:209], v[190:193], v[64:67]
	s_barrier
	s_mov_b32 m0, s39
	v_lshl_add_u64 v[210:211], s[18:19], 0, v[156:157]
	global_load_lds_dwordx4 v[210:211], off
	s_add_i32 m0, s39, 0x2000
	v_lshl_add_u64 v[210:211], s[18:19], 0, v[158:159]
	global_load_lds_dwordx4 v[210:211], off
	s_mov_b32 m0, s29
	v_lshl_add_u64 v[210:211], s[16:17], 0, v[156:157]
	global_load_lds_dwordx4 v[210:211], off nt
	s_mov_b32 m0, s30
	v_lshl_add_u64 v[210:211], s[16:17], 0, v[158:159]
	global_load_lds_dwordx4 v[210:211], off nt
	s_add_u32 s14, s14, 0x84000
	s_addc_u32 s15, s15, 0
	s_add_i32 s16, s40, s23
	s_mov_b32 m0, s16
	v_lshl_add_u64 v[210:211], s[14:15], 0, v[156:157]
	global_load_lds_dwordx4 v[210:211], off
	s_add_i32 m0, s16, 0x2000
	v_lshl_add_u64 v[210:211], s[14:15], 0, v[158:159]
	global_load_lds_dwordx4 v[210:211], off
	ds_read_b128 v[144:147], v172 offset:49152
	ds_read_b128 v[166:169], v172 offset:51200
	ds_read_b128 v[178:181], v172 offset:53248
	ds_read_b128 v[186:189], v172 offset:55296
	ds_read_b128 v[148:151], v172 offset:50176
	ds_read_b128 v[174:177], v172 offset:52224
	ds_read_b128 v[182:185], v172 offset:54272
	ds_read_b128 v[190:193], v172 offset:56320
	s_waitcnt vmcnt(6)
	s_waitcnt lgkmcnt(0)
	s_barrier
	v_mfma_f32_16x16x32_bf16 v[60:63], v[128:131], v[144:147], v[60:63]
	s_setprio 1
	v_mfma_f32_16x16x32_bf16 v[56:59], v[136:139], v[144:147], v[56:59]
	v_mfma_f32_16x16x32_bf16 v[44:47], v[128:131], v[166:169], v[44:47]
	v_mfma_f32_16x16x32_bf16 v[40:43], v[136:139], v[166:169], v[40:43]
	v_mfma_f32_16x16x32_bf16 v[28:31], v[128:131], v[178:181], v[28:31]
	v_mfma_f32_16x16x32_bf16 v[24:27], v[136:139], v[178:181], v[24:27]
	v_mfma_f32_16x16x32_bf16 v[12:15], v[128:131], v[186:189], v[12:15]
	v_mfma_f32_16x16x32_bf16 v[8:11], v[136:139], v[186:189], v[8:11]
	v_mfma_f32_16x16x32_bf16 v[60:63], v[132:135], v[148:151], v[60:63]
	v_mfma_f32_16x16x32_bf16 v[56:59], v[140:143], v[148:151], v[56:59]
	v_mfma_f32_16x16x32_bf16 v[44:47], v[132:135], v[174:177], v[44:47]
	v_mfma_f32_16x16x32_bf16 v[40:43], v[140:143], v[174:177], v[40:43]
	v_mfma_f32_16x16x32_bf16 v[28:31], v[132:135], v[182:185], v[28:31]
	v_mfma_f32_16x16x32_bf16 v[24:27], v[140:143], v[182:185], v[24:27]
	v_mfma_f32_16x16x32_bf16 v[12:15], v[132:135], v[190:193], v[12:15]
	v_mfma_f32_16x16x32_bf16 v[8:11], v[140:143], v[190:193], v[8:11]
	v_mfma_f32_16x16x32_bf16 v[52:55], v[194:197], v[144:147], v[52:55]
	v_mfma_f32_16x16x32_bf16 v[48:51], v[202:205], v[144:147], v[48:51]
	s_add_i32 s38, s38, 2
	s_add_u32 s12, s12, 0x8000
	s_addc_u32 s13, s13, 0
	s_add_u32 s36, s36, 0x8000
	s_addc_u32 s37, s37, 0
	v_mfma_f32_16x16x32_bf16 v[36:39], v[194:197], v[166:169], v[36:39]
	v_mfma_f32_16x16x32_bf16 v[32:35], v[202:205], v[166:169], v[32:35]
	v_mfma_f32_16x16x32_bf16 v[20:23], v[194:197], v[178:181], v[20:23]
	v_mfma_f32_16x16x32_bf16 v[16:19], v[202:205], v[178:181], v[16:19]
	v_mfma_f32_16x16x32_bf16 v[4:7], v[194:197], v[186:189], v[4:7]
	v_mfma_f32_16x16x32_bf16 v[0:3], v[202:205], v[186:189], v[0:3]
	v_mfma_f32_16x16x32_bf16 v[52:55], v[198:201], v[148:151], v[52:55]
	v_mfma_f32_16x16x32_bf16 v[48:51], v[206:209], v[148:151], v[48:51]
	v_mfma_f32_16x16x32_bf16 v[36:39], v[198:201], v[174:177], v[36:39]
	v_mfma_f32_16x16x32_bf16 v[32:35], v[206:209], v[174:177], v[32:35]
	v_mfma_f32_16x16x32_bf16 v[20:23], v[198:201], v[182:185], v[20:23]
	v_mfma_f32_16x16x32_bf16 v[16:19], v[206:209], v[182:185], v[16:19]
	v_mfma_f32_16x16x32_bf16 v[4:7], v[198:201], v[190:193], v[4:7]
	s_cmp_gt_u32 s38, 29
	s_setprio 0
	v_mfma_f32_16x16x32_bf16 v[0:3], v[206:209], v[190:193], v[0:3]
	s_barrier
	s_cbranch_scc0 .LBB0_247
